# prologue: read-once f32 weight and x loads marked nt
# baseline (speedup 1.0000x reference)
; #define LAS __attribute__((address_space(3)))
; __device__ __forceinline__ void transpose_item(const float* W, int K, int N, bf16_t* WT, const float* g, LAS float* scr, int item, int lane) {
;     const int nblk = N / 32, kb = item / nblk, nb = item % nblk, k0 = 64 * kb, n0 = 32 * nb;
;     float wv[32], gl[32];
; #pragma unroll
;     for (int i = 0; i < 32; ++i) { const int kk = 2 * i + (lane >> 5); wv[i] = W[(size_t)(k0 + kk) * N + n0 + (lane & 31)]; gl[i] = g ? g[k0 + kk] : 1.0f; }
; #pragma unroll
;     for (int i = 0; i < 32; ++i) { const int kk = 2 * i + (lane >> 5); scr[kk * 33 + (lane & 31)] = wv[i] * gl[i]; }
; __global__ void __launch_bounds__(512, 2) fwd_kernel(Args a_unused) {
;     ...
;             transpose_item(A->w_out + (size_t)l * 1024 * 1024, 1024, 1024, WOUT + (size_t)l * 1024 * 1024, nullptr, scr, r, lane);
.LBB0_9:
	s_mul_hi_i32 s4, s64, 0x94f2095
	s_lshr_b32 s5, s4, 31
	s_ashr_i32 s4, s4, 8
	s_add_i32 s22, s4, s5
	s_mul_i32 s12, s22, 0xffffe480
	s_add_i32 s12, s12, s64
	s_cmpk_gt_i32 s12, 0x167f
	s_mov_b64 s[4:5], -1
	s_cbranch_scc0 .LBB0_23
	s_cmpk_gt_u32 s12, 0x177f
	s_cbranch_scc0 .LBB0_20
	s_cmpk_gt_u32 s12, 0x187f
	s_cbranch_scc0 .LBB0_17
	s_ashr_i32 s23, s22, 31
	s_cmpk_gt_u32 s12, 0x197f
	s_cbranch_scc0 .LBB0_14
	s_load_dwordx2 s[4:5], s[8:9], 0x38
	s_lshl_b64 s[6:7], s[22:23], 22
	v_mov_b32_e32 v11, v7
	v_mov_b32_e32 v29, v7
	v_mov_b32_e32 v31, v7
	s_waitcnt lgkmcnt(0)
	s_add_u32 s13, s4, s6
	s_addc_u32 s25, s5, s7
	s_lshl_b64 s[6:7], s[22:23], 21
	s_add_u32 s5, s29, s6
	s_addc_u32 s6, s30, s7
	s_lshl_b32 s4, s12, 1
	s_lshl_b32 s7, s64, 5
	s_andn2_b32 s4, s4, 63
	s_add_i32 s16, s4, 0xffffcd00
	s_and_b32 s4, s7, 0x3e0
	s_lshl_b32 s7, s4, 2
	v_or_b32_e32 v10, s16, v1
	s_add_u32 s24, s13, s7
	s_addc_u32 s25, s25, 0
	v_or_b32_e32 v28, 2, v10
	v_or_b32_e32 v30, 4, v10
	v_or_b32_e32 v32, 6, v10
	v_mov_b32_e32 v33, v7
	v_or_b32_e32 v34, 8, v10
	v_mov_b32_e32 v35, v7
	v_or_b32_e32 v36, 10, v10
	v_mov_b32_e32 v37, v7
	v_or_b32_e32 v38, 12, v10
	v_mov_b32_e32 v39, v7
	v_or_b32_e32 v40, 14, v10
	v_mov_b32_e32 v41, v7
	v_lshl_add_u64 v[12:13], s[24:25], 0, v[6:7]
	v_lshlrev_b64 v[14:15], 12, v[10:11]
	v_lshlrev_b64 v[28:29], 12, v[28:29]
	v_lshlrev_b64 v[30:31], 12, v[30:31]
	v_lshlrev_b64 v[32:33], 12, v[32:33]
	v_lshlrev_b64 v[34:35], 12, v[34:35]
	v_lshlrev_b64 v[36:37], 12, v[36:37]
	v_lshlrev_b64 v[38:39], 12, v[38:39]
	v_lshlrev_b64 v[40:41], 12, v[40:41]
	v_lshl_add_u64 v[14:15], v[12:13], 0, v[14:15]
	v_lshl_add_u64 v[28:29], v[12:13], 0, v[28:29]
	v_lshl_add_u64 v[30:31], v[12:13], 0, v[30:31]
	v_lshl_add_u64 v[32:33], v[12:13], 0, v[32:33]
	v_lshl_add_u64 v[34:35], v[12:13], 0, v[34:35]
	v_lshl_add_u64 v[36:37], v[12:13], 0, v[36:37]
	v_lshl_add_u64 v[38:39], v[12:13], 0, v[38:39]
	v_lshl_add_u64 v[40:41], v[12:13], 0, v[40:41]
	global_load_dword v9, v[14:15], off nt
	global_load_dword v42, v[28:29], off nt
	global_load_dword v43, v[30:31], off nt
	global_load_dword v44, v[32:33], off nt
	global_load_dword v45, v[34:35], off nt
	global_load_dword v46, v[36:37], off nt
	global_load_dword v47, v[38:39], off nt
	global_load_dword v48, v[40:41], off nt
	v_or_b32_e32 v14, 16, v10
	v_mov_b32_e32 v15, v7
	v_or_b32_e32 v28, 18, v10
	v_mov_b32_e32 v29, v7
	v_or_b32_e32 v30, 20, v10
	v_mov_b32_e32 v31, v7
	v_or_b32_e32 v32, 22, v10
	v_mov_b32_e32 v33, v7
	v_or_b32_e32 v34, 24, v10
	v_mov_b32_e32 v35, v7
	v_or_b32_e32 v36, 26, v10
	v_mov_b32_e32 v37, v7
	v_or_b32_e32 v38, 28, v10
	v_mov_b32_e32 v39, v7
	v_or_b32_e32 v40, 30, v10
	v_mov_b32_e32 v41, v7
	v_lshlrev_b64 v[14:15], 12, v[14:15]
	v_lshlrev_b64 v[28:29], 12, v[28:29]
	v_lshlrev_b64 v[30:31], 12, v[30:31]
	v_lshlrev_b64 v[32:33], 12, v[32:33]
	v_lshlrev_b64 v[34:35], 12, v[34:35]
	v_lshlrev_b64 v[36:37], 12, v[36:37]
	v_lshlrev_b64 v[38:39], 12, v[38:39]
	v_lshlrev_b64 v[40:41], 12, v[40:41]
	v_lshl_add_u64 v[14:15], v[12:13], 0, v[14:15]
	v_lshl_add_u64 v[28:29], v[12:13], 0, v[28:29]
	v_lshl_add_u64 v[30:31], v[12:13], 0, v[30:31]
	v_lshl_add_u64 v[32:33], v[12:13], 0, v[32:33]
	v_lshl_add_u64 v[34:35], v[12:13], 0, v[34:35]
	v_lshl_add_u64 v[36:37], v[12:13], 0, v[36:37]
	v_lshl_add_u64 v[38:39], v[12:13], 0, v[38:39]
	v_lshl_add_u64 v[40:41], v[12:13], 0, v[40:41]
	global_load_dword v49, v[14:15], off nt
	global_load_dword v50, v[28:29], off nt
	global_load_dword v51, v[30:31], off nt
	global_load_dword v52, v[32:33], off nt
	global_load_dword v53, v[34:35], off nt
	global_load_dword v54, v[36:37], off nt
	global_load_dword v55, v[38:39], off nt
	global_load_dword v56, v[40:41], off nt
	v_or_b32_e32 v14, 32, v10
	v_mov_b32_e32 v15, v7
	v_or_b32_e32 v28, 34, v10
	v_mov_b32_e32 v29, v7
	v_or_b32_e32 v30, 36, v10
	v_mov_b32_e32 v31, v7
	v_or_b32_e32 v32, 38, v10
	v_mov_b32_e32 v33, v7
	v_or_b32_e32 v34, 40, v10
	v_mov_b32_e32 v35, v7
	v_or_b32_e32 v36, 42, v10
	v_mov_b32_e32 v37, v7
	v_or_b32_e32 v38, 44, v10
	v_mov_b32_e32 v39, v7
	v_or_b32_e32 v40, 46, v10
	v_mov_b32_e32 v41, v7
	v_lshlrev_b64 v[14:15], 12, v[14:15]
	v_lshlrev_b64 v[28:29], 12, v[28:29]
	v_lshlrev_b64 v[30:31], 12, v[30:31]
	v_lshlrev_b64 v[32:33], 12, v[32:33]
	v_lshlrev_b64 v[34:35], 12, v[34:35]
	v_lshlrev_b64 v[36:37], 12, v[36:37]
	v_lshlrev_b64 v[38:39], 12, v[38:39]
	v_lshlrev_b64 v[40:41], 12, v[40:41]
	v_lshl_add_u64 v[14:15], v[12:13], 0, v[14:15]
	v_lshl_add_u64 v[28:29], v[12:13], 0, v[28:29]
	v_lshl_add_u64 v[30:31], v[12:13], 0, v[30:31]
	v_lshl_add_u64 v[32:33], v[12:13], 0, v[32:33]
	v_lshl_add_u64 v[34:35], v[12:13], 0, v[34:35]
	v_lshl_add_u64 v[36:37], v[12:13], 0, v[36:37]
	v_lshl_add_u64 v[38:39], v[12:13], 0, v[38:39]
	v_lshl_add_u64 v[40:41], v[12:13], 0, v[40:41]
	global_load_dword v57, v[14:15], off nt
	global_load_dword v58, v[28:29], off nt
	global_load_dword v59, v[30:31], off nt
	global_load_dword v60, v[32:33], off nt
	global_load_dword v61, v[34:35], off nt
	global_load_dword v62, v[36:37], off nt
	global_load_dword v63, v[38:39], off nt
	s_nop 0
	global_load_dword v40, v[40:41], off nt
	v_or_b32_e32 v14, 48, v10
	v_mov_b32_e32 v15, v7
	v_or_b32_e32 v28, 50, v10
	v_mov_b32_e32 v29, v7
	v_or_b32_e32 v30, 52, v10
	v_mov_b32_e32 v31, v7
	v_or_b32_e32 v32, 54, v10
	v_or_b32_e32 v34, 56, v10
	v_or_b32_e32 v36, 58, v10
	v_or_b32_e32 v38, 60, v10
	v_or_b32_e32 v10, 62, v10
	v_lshlrev_b64 v[14:15], 12, v[14:15]
	v_lshlrev_b64 v[28:29], 12, v[28:29]
	v_lshlrev_b64 v[30:31], 12, v[30:31]
	v_mov_b32_e32 v33, v7
	v_mov_b32_e32 v35, v7
	v_mov_b32_e32 v37, v7
	v_mov_b32_e32 v39, v7
	v_lshlrev_b64 v[10:11], 12, v[10:11]
	v_lshl_add_u64 v[14:15], v[12:13], 0, v[14:15]
	v_lshl_add_u64 v[28:29], v[12:13], 0, v[28:29]
	v_lshl_add_u64 v[30:31], v[12:13], 0, v[30:31]
	v_lshlrev_b64 v[32:33], 12, v[32:33]
	v_lshlrev_b64 v[34:35], 12, v[34:35]
	v_lshlrev_b64 v[36:37], 12, v[36:37]
	v_lshlrev_b64 v[38:39], 12, v[38:39]
	v_lshl_add_u64 v[10:11], v[12:13], 0, v[10:11]
	v_lshl_add_u64 v[32:33], v[12:13], 0, v[32:33]
	v_lshl_add_u64 v[34:35], v[12:13], 0, v[34:35]
	v_lshl_add_u64 v[36:37], v[12:13], 0, v[36:37]
	v_lshl_add_u64 v[38:39], v[12:13], 0, v[38:39]
	global_load_dword v12, v[14:15], off nt
	global_load_dword v13, v[28:29], off nt
	s_nop 0
	global_load_dword v14, v[30:31], off nt
	global_load_dword v15, v[32:33], off nt
	global_load_dword v28, v[34:35], off nt
	global_load_dword v29, v[36:37], off nt
	s_nop 0
	global_load_dword v30, v[38:39], off nt
	s_nop 0
	global_load_dword v10, v[10:11], off nt
	s_waitcnt vmcnt(30)
; #define LAS __attribute__((address_space(3)))
; __device__ __forceinline__ unsigned cvtpk(float lo, float hi) { f32x2 v = {lo, hi}; bf16x2_t b = __builtin_convertvector(v, bf16x2_t); return __builtin_bit_cast(unsigned, b); }
; __device__ __forceinline__ void transpose_item(const float* W, int K, int N, bf16_t* WT, const float* g, LAS float* scr, int item, int lane) {
;     ...
;     for (int i = 0; i < 32; ++i) { const int kk = 2 * i + (lane >> 5); scr[kk * 33 + (lane & 31)] = wv[i] * gl[i]; }
;     asm volatile("s_waitcnt lgkmcnt(0)" ::: "memory");
;     const int c = lane & 7;
; #pragma unroll
;     for (int j = 0; j < 4; ++j) { const int n = (lane >> 3) + 8 * j; const LAS float* s = scr + (8 * c) * 33 + n;
;         u32x4 o; o.x = cvtpk(s[0 * 33], s[1 * 33]); o.y = cvtpk(s[2 * 33], s[3 * 33]); o.z = cvtpk(s[4 * 33], s[5 * 33]); o.w = cvtpk(s[6 * 33], s[7 * 33]);
;         *(u32x4*)(WT + (size_t)(n0 + n) * K + k0 + 8 * c) = o; }
; __global__ void __launch_bounds__(512, 2) fwd_kernel(Args a_unused) {
;     ...
;             if (r < I_O) { transpose_item(A->w_oc + (size_t)l * 512 * 1024, 512, 1024, WO3 + (size_t)(l * 3 + 2) * 1024 * 512, nullptr, scr, r, lane); continue; } r -= I_O;
	ds_write2_b32 v3, v9, v42 offset1:66
	s_waitcnt vmcnt(28)
	ds_write2_b32 v3, v43, v44 offset0:132 offset1:198
	s_waitcnt vmcnt(26)
	ds_write2_b32 v20, v45, v46 offset0:8 offset1:74
	s_waitcnt vmcnt(24)
	ds_write2_b32 v20, v47, v48 offset0:140 offset1:206
	s_waitcnt vmcnt(22)
	ds_write2_b32 v21, v49, v50 offset0:16 offset1:82
	s_waitcnt vmcnt(20)
	ds_write2_b32 v21, v51, v52 offset0:148 offset1:214
	s_waitcnt vmcnt(18)
	ds_write2_b32 v22, v53, v54 offset0:24 offset1:90
	s_waitcnt vmcnt(16)
	ds_write2_b32 v22, v55, v56 offset0:156 offset1:222
	s_waitcnt vmcnt(14)
	ds_write2_b32 v23, v57, v58 offset0:32 offset1:98
	s_waitcnt vmcnt(12)
	ds_write2_b32 v23, v59, v60 offset0:164 offset1:230
	s_waitcnt vmcnt(10)
	ds_write2_b32 v24, v61, v62 offset0:40 offset1:106
	s_waitcnt vmcnt(8)
	ds_write2_b32 v24, v63, v40 offset0:172 offset1:238
	s_waitcnt vmcnt(6)
	ds_write2_b32 v25, v12, v13 offset0:48 offset1:114
	s_waitcnt vmcnt(4)
	ds_write2_b32 v25, v14, v15 offset0:180 offset1:246
	s_waitcnt vmcnt(2)
	ds_write2_b32 v26, v28, v29 offset0:56 offset1:122
	s_waitcnt vmcnt(0)
	ds_write2_b32 v26, v30, v10 offset0:188 offset1:254
	s_waitcnt lgkmcnt(0)
	s_lshl_b64 s[24:25], s[16:17], 1
	ds_read2_b32 v[14:15], v16 offset0:33 offset1:41
	ds_read2_b32 v[28:29], v16 offset1:8
	ds_read2_b32 v[30:31], v16 offset0:66 offset1:74
	ds_read2_b32 v[32:33], v16 offset0:99 offset1:107
	ds_read2_b32 v[34:35], v16 offset0:132 offset1:140
	ds_read2_b32 v[36:37], v16 offset0:165 offset1:173
	ds_read2_b32 v[38:39], v16 offset0:198 offset1:206
	ds_read2_b32 v[40:41], v16 offset0:231 offset1:239
	s_add_u32 s24, s5, s24
	s_addc_u32 s25, s6, s25
	v_mov_b32_e32 v9, v7
	v_lshl_add_u64 v[42:43], s[24:25], 0, v[8:9]
	v_or_b32_e32 v9, s4, v5
	v_lshlrev_b32_e32 v44, 11, v9
	v_mov_b32_e32 v45, v7
	s_waitcnt lgkmcnt(6)
	v_cvt_pk_bf16_f32 v10, v28, v14
	s_waitcnt lgkmcnt(4)
	v_cvt_pk_bf16_f32 v11, v30, v32
	s_waitcnt lgkmcnt(2)
	v_cvt_pk_bf16_f32 v12, v34, v36
	s_waitcnt lgkmcnt(0)
	v_cvt_pk_bf16_f32 v13, v38, v40
	v_lshl_add_u64 v[44:45], v[42:43], 0, v[44:45]
	global_store_dwordx4 v[44:45], v[10:13], off
	v_or_b32_e32 v9, s4, v17
	v_lshlrev_b32_e32 v14, 11, v9
	v_cvt_pk_bf16_f32 v10, v29, v15
	v_cvt_pk_bf16_f32 v11, v31, v33
	v_cvt_pk_bf16_f32 v12, v35, v37
	v_cvt_pk_bf16_f32 v13, v39, v41
	ds_read2_b32 v[28:29], v16 offset0:49 offset1:57
	ds_read2_b32 v[30:31], v16 offset0:16 offset1:24
	ds_read2_b32 v[32:33], v16 offset0:82 offset1:90
	ds_read2_b32 v[34:35], v16 offset0:115 offset1:123
	ds_read2_b32 v[36:37], v16 offset0:148 offset1:156
	ds_read2_b32 v[38:39], v16 offset0:181 offset1:189
	ds_read2_b32 v[40:41], v16 offset0:214 offset1:222
	ds_read2_b32 v[44:45], v16 offset0:247 offset1:255
	v_mov_b32_e32 v15, v7
	v_lshl_add_u64 v[14:15], v[42:43], 0, v[14:15]
	v_or_b32_e32 v9, s4, v18
	global_store_dwordx4 v[14:15], v[10:13], off
	v_lshlrev_b32_e32 v14, 11, v9
	v_mov_b32_e32 v15, v7
	s_waitcnt lgkmcnt(6)
	v_cvt_pk_bf16_f32 v10, v30, v28
	s_waitcnt lgkmcnt(4)
	v_cvt_pk_bf16_f32 v11, v32, v34
	s_waitcnt lgkmcnt(2)
	v_cvt_pk_bf16_f32 v12, v36, v38
	s_waitcnt lgkmcnt(0)
	v_cvt_pk_bf16_f32 v13, v40, v44
	v_lshl_add_u64 v[14:15], v[42:43], 0, v[14:15]
	v_or_b32_e32 v9, s4, v19
	global_store_dwordx4 v[14:15], v[10:13], off
	v_lshlrev_b32_e32 v14, 11, v9
	v_mov_b32_e32 v15, v7
	v_cvt_pk_bf16_f32 v10, v31, v29
	v_cvt_pk_bf16_f32 v11, v33, v35
	v_cvt_pk_bf16_f32 v12, v37, v39
	v_cvt_pk_bf16_f32 v13, v41, v45
	v_lshl_add_u64 v[14:15], v[42:43], 0, v[14:15]
	global_store_dwordx4 v[14:15], v[10:13], off
	s_waitcnt lgkmcnt(0)
	s_mov_b64 s[4:5], 0
.LBB0_14:
	s_andn2_b64 vcc, exec, s[4:5]
	s_cbranch_vccnz .LBB0_16
	s_load_dwordx2 s[4:5], s[8:9], 0x30
	s_lshl_b64 s[6:7], s[22:23], 21
	s_mul_i32 s24, s22, 3
	v_mov_b32_e32 v13, v7
	s_waitcnt lgkmcnt(0)
	s_add_u32 s13, s4, s6
	s_addc_u32 s16, s5, s7
	s_ashr_i32 s25, s24, 31
	s_lshl_b64 s[6:7], s[24:25], 20
	s_add_u32 s5, s27, s6
	s_addc_u32 s6, s28, s7
	s_lshl_b32 s4, s12, 1
	s_and_b32 s23, s4, 0x1c0
	s_lshl_b32 s4, s64, 5
	s_and_b32 s4, s4, 0x3e0
	s_xor_b32 s7, s23, 0x100
	v_bitop3_b32 v9, s23, v1, v27 bitop3:0xde
	s_lshl_b32 s23, s4, 2
	s_add_u32 s24, s13, s23
	s_addc_u32 s25, s16, 0
	v_lshl_add_u64 v[10:11], s[24:25], 0, v[6:7]
	v_lshlrev_b32_e32 v12, 12, v9
	v_lshl_add_u64 v[10:11], v[10:11], 0, v[12:13]
	v_add_co_u32_e32 v12, vcc, s31, v10
	s_lshl_b32 s7, s7, 1
	s_nop 0
	v_addc_co_u32_e32 v13, vcc, 0, v11, vcc
	v_add_co_u32_e32 v14, vcc, s33, v10
	s_add_u32 s24, s5, s7
	s_nop 0
	v_addc_co_u32_e32 v15, vcc, 0, v11, vcc
	v_add_co_u32_e32 v28, vcc, s34, v10
	s_addc_u32 s25, s6, 0
	s_nop 0
	v_addc_co_u32_e32 v29, vcc, 0, v11, vcc
	v_add_co_u32_e32 v30, vcc, s35, v10
	s_nop 1
	v_addc_co_u32_e32 v31, vcc, 0, v11, vcc
	v_add_co_u32_e32 v32, vcc, s36, v10
	s_nop 1
	v_addc_co_u32_e32 v33, vcc, 0, v11, vcc
	v_add_co_u32_e32 v34, vcc, s37, v10
	s_nop 1
	v_addc_co_u32_e32 v35, vcc, 0, v11, vcc
	v_add_co_u32_e32 v36, vcc, s38, v10
	s_nop 1
	v_addc_co_u32_e32 v37, vcc, 0, v11, vcc
	global_load_dword v9, v[10:11], off nt
	global_load_dword v40, v[12:13], off nt
	global_load_dword v41, v[14:15], off nt
	global_load_dword v42, v[28:29], off nt
	global_load_dword v43, v[30:31], off nt
	global_load_dword v44, v[32:33], off nt
	global_load_dword v45, v[34:35], off nt
	global_load_dword v46, v[36:37], off nt
	v_add_co_u32_e32 v12, vcc, s39, v10
	s_nop 1
	v_addc_co_u32_e32 v13, vcc, 0, v11, vcc
	v_add_co_u32_e32 v14, vcc, s40, v10
	s_nop 1
	v_addc_co_u32_e32 v15, vcc, 0, v11, vcc
	v_add_co_u32_e32 v28, vcc, s41, v10
	s_nop 1
	v_addc_co_u32_e32 v29, vcc, 0, v11, vcc
	v_add_co_u32_e32 v30, vcc, s42, v10
	s_nop 1
	v_addc_co_u32_e32 v31, vcc, 0, v11, vcc
; #define LAS __attribute__((address_space(3)))
; __device__ __forceinline__ unsigned cvtpk(float lo, float hi) { f32x2 v = {lo, hi}; bf16x2_t b = __builtin_convertvector(v, bf16x2_t); return __builtin_bit_cast(unsigned, b); }
; __device__ __forceinline__ void transpose_item(const float* W, int K, int N, bf16_t* WT, const float* g, LAS float* scr, int item, int lane) {
;     ...
;     for (int i = 0; i < 32; ++i) { const int kk = 2 * i + (lane >> 5); wv[i] = W[(size_t)(k0 + kk) * N + n0 + (lane & 31)]; gl[i] = g ? g[k0 + kk] : 1.0f; }
; #pragma unroll
;     for (int i = 0; i < 32; ++i) { const int kk = 2 * i + (lane >> 5); scr[kk * 33 + (lane & 31)] = wv[i] * gl[i]; }
;     asm volatile("s_waitcnt lgkmcnt(0)" ::: "memory");
;     const int c = lane & 7;
; #pragma unroll
;     for (int j = 0; j < 4; ++j) { const int n = (lane >> 3) + 8 * j; const LAS float* s = scr + (8 * c) * 33 + n;
;         u32x4 o; o.x = cvtpk(s[0 * 33], s[1 * 33]); o.y = cvtpk(s[2 * 33], s[3 * 33]); o.z = cvtpk(s[4 * 33], s[5 * 33]); o.w = cvtpk(s[6 * 33], s[7 * 33]);
;         *(u32x4*)(WT + (size_t)(n0 + n) * K + k0 + 8 * c) = o; }
	v_add_co_u32_e32 v32, vcc, s43, v10
	s_nop 1
	v_addc_co_u32_e32 v33, vcc, 0, v11, vcc
	v_add_co_u32_e32 v34, vcc, s44, v10
	s_nop 1
	v_addc_co_u32_e32 v35, vcc, 0, v11, vcc
	v_add_co_u32_e32 v36, vcc, s45, v10
	s_nop 1
	v_addc_co_u32_e32 v37, vcc, 0, v11, vcc
	v_add_co_u32_e32 v38, vcc, s46, v10
	s_nop 1
	v_addc_co_u32_e32 v39, vcc, 0, v11, vcc
	global_load_dword v47, v[12:13], off nt
	global_load_dword v48, v[14:15], off nt
	global_load_dword v49, v[28:29], off nt
	global_load_dword v50, v[30:31], off nt
	global_load_dword v51, v[32:33], off nt
	global_load_dword v52, v[34:35], off nt
	global_load_dword v53, v[36:37], off nt
	global_load_dword v54, v[38:39], off nt
	v_add_co_u32_e32 v12, vcc, s47, v10
	s_nop 1
	v_addc_co_u32_e32 v13, vcc, 0, v11, vcc
	v_add_co_u32_e32 v14, vcc, s48, v10
	s_nop 1
	v_addc_co_u32_e32 v15, vcc, 0, v11, vcc
	v_add_co_u32_e32 v28, vcc, s49, v10
	s_nop 1
	v_addc_co_u32_e32 v29, vcc, 0, v11, vcc
	v_add_co_u32_e32 v30, vcc, s50, v10
	s_nop 1
	v_addc_co_u32_e32 v31, vcc, 0, v11, vcc
	v_add_co_u32_e32 v32, vcc, s51, v10
	s_nop 1
	v_addc_co_u32_e32 v33, vcc, 0, v11, vcc
	v_add_co_u32_e32 v34, vcc, s52, v10
	s_nop 1
	v_addc_co_u32_e32 v35, vcc, 0, v11, vcc
	v_add_co_u32_e32 v36, vcc, s53, v10
	s_nop 1
	v_addc_co_u32_e32 v37, vcc, 0, v11, vcc
	v_add_co_u32_e32 v38, vcc, s54, v10
	s_nop 1
	v_addc_co_u32_e32 v39, vcc, 0, v11, vcc
	global_load_dword v55, v[12:13], off nt
	global_load_dword v56, v[14:15], off nt
	global_load_dword v57, v[28:29], off nt
	global_load_dword v58, v[30:31], off nt
	global_load_dword v59, v[32:33], off nt
	global_load_dword v60, v[34:35], off nt
	global_load_dword v61, v[36:37], off nt
	s_nop 0
	global_load_dword v38, v[38:39], off nt
	v_add_co_u32_e32 v12, vcc, s55, v10
	s_nop 1
	v_addc_co_u32_e32 v13, vcc, 0, v11, vcc
	v_add_co_u32_e32 v14, vcc, s56, v10
	s_nop 1
	v_addc_co_u32_e32 v15, vcc, 0, v11, vcc
	v_add_co_u32_e32 v28, vcc, s57, v10
	s_nop 1
	v_addc_co_u32_e32 v29, vcc, 0, v11, vcc
	v_add_co_u32_e32 v30, vcc, s58, v10
	s_nop 1
	v_addc_co_u32_e32 v31, vcc, 0, v11, vcc
	v_add_co_u32_e32 v32, vcc, s59, v10
	s_nop 1
	v_addc_co_u32_e32 v33, vcc, 0, v11, vcc
	v_add_co_u32_e32 v34, vcc, s60, v10
	s_nop 1
	v_addc_co_u32_e32 v35, vcc, 0, v11, vcc
	v_add_co_u32_e32 v36, vcc, s61, v10
	s_nop 1
	v_addc_co_u32_e32 v37, vcc, 0, v11, vcc
	v_add_co_u32_e32 v10, vcc, s62, v10
	s_nop 1
	v_addc_co_u32_e32 v11, vcc, 0, v11, vcc
	global_load_dword v12, v[12:13], off nt
	s_nop 0
	global_load_dword v13, v[14:15], off nt
	s_nop 0
	global_load_dword v14, v[28:29], off nt
	global_load_dword v15, v[30:31], off nt
	s_nop 0
	global_load_dword v28, v[32:33], off nt
	global_load_dword v29, v[34:35], off nt
	global_load_dword v30, v[36:37], off nt
	s_nop 0
	global_load_dword v10, v[10:11], off nt
	s_waitcnt vmcnt(30)
	ds_write2_b32 v3, v9, v40 offset1:66
	s_waitcnt vmcnt(28)
	ds_write2_b32 v3, v41, v42 offset0:132 offset1:198
	s_waitcnt vmcnt(26)
	ds_write2_b32 v20, v43, v44 offset0:8 offset1:74
	s_waitcnt vmcnt(24)
	ds_write2_b32 v20, v45, v46 offset0:140 offset1:206
	s_waitcnt vmcnt(22)
	ds_write2_b32 v21, v47, v48 offset0:16 offset1:82
	s_waitcnt vmcnt(20)
	ds_write2_b32 v21, v49, v50 offset0:148 offset1:214
	s_waitcnt vmcnt(18)
	ds_write2_b32 v22, v51, v52 offset0:24 offset1:90
	s_waitcnt vmcnt(16)
	ds_write2_b32 v22, v53, v54 offset0:156 offset1:222
	s_waitcnt vmcnt(14)
	ds_write2_b32 v23, v55, v56 offset0:32 offset1:98
	s_waitcnt vmcnt(12)
	ds_write2_b32 v23, v57, v58 offset0:164 offset1:230
	s_waitcnt vmcnt(10)
	ds_write2_b32 v24, v59, v60 offset0:40 offset1:106
	s_waitcnt vmcnt(8)
	ds_write2_b32 v24, v61, v38 offset0:172 offset1:238
	s_waitcnt vmcnt(6)
	ds_write2_b32 v25, v12, v13 offset0:48 offset1:114
	s_waitcnt vmcnt(4)
	ds_write2_b32 v25, v14, v15 offset0:180 offset1:246
	s_waitcnt vmcnt(2)
	ds_write2_b32 v26, v28, v29 offset0:56 offset1:122
	s_waitcnt vmcnt(0)
	ds_write2_b32 v26, v30, v10 offset0:188 offset1:254
	s_waitcnt lgkmcnt(0)
	ds_read2_b32 v[14:15], v16 offset0:33 offset1:41
	ds_read2_b32 v[28:29], v16 offset1:8
	ds_read2_b32 v[30:31], v16 offset0:66 offset1:74
	ds_read2_b32 v[32:33], v16 offset0:99 offset1:107
	ds_read2_b32 v[34:35], v16 offset0:132 offset1:140
	ds_read2_b32 v[36:37], v16 offset0:165 offset1:173
	ds_read2_b32 v[38:39], v16 offset0:198 offset1:206
	ds_read2_b32 v[40:41], v16 offset0:231 offset1:239
	v_mov_b32_e32 v9, v7
	v_lshl_add_u64 v[10:11], s[24:25], 0, v[8:9]
	v_or_b32_e32 v9, s4, v5
	v_lshl_add_u64 v[42:43], v[10:11], 0, s[20:21]
	v_lshlrev_b32_e32 v44, 10, v9
	v_mov_b32_e32 v45, v7
	s_waitcnt lgkmcnt(6)
	v_cvt_pk_bf16_f32 v10, v28, v14
	s_waitcnt lgkmcnt(4)
	v_cvt_pk_bf16_f32 v11, v30, v32
	s_waitcnt lgkmcnt(2)
	v_cvt_pk_bf16_f32 v12, v34, v36
	s_waitcnt lgkmcnt(0)
	v_cvt_pk_bf16_f32 v13, v38, v40
	v_lshl_add_u64 v[44:45], v[42:43], 0, v[44:45]
	global_store_dwordx4 v[44:45], v[10:13], off
	v_or_b32_e32 v9, s4, v17
	v_lshlrev_b32_e32 v14, 10, v9
	v_cvt_pk_bf16_f32 v10, v29, v15
	v_cvt_pk_bf16_f32 v11, v31, v33
	v_cvt_pk_bf16_f32 v12, v35, v37
	v_cvt_pk_bf16_f32 v13, v39, v41
	ds_read2_b32 v[28:29], v16 offset0:49 offset1:57
	ds_read2_b32 v[30:31], v16 offset0:16 offset1:24
	ds_read2_b32 v[32:33], v16 offset0:82 offset1:90
	ds_read2_b32 v[34:35], v16 offset0:115 offset1:123
	ds_read2_b32 v[36:37], v16 offset0:148 offset1:156
	ds_read2_b32 v[38:39], v16 offset0:181 offset1:189
	ds_read2_b32 v[40:41], v16 offset0:214 offset1:222
	ds_read2_b32 v[44:45], v16 offset0:247 offset1:255
	v_mov_b32_e32 v15, v7
	v_lshl_add_u64 v[14:15], v[42:43], 0, v[14:15]
	v_or_b32_e32 v9, s4, v18
	global_store_dwordx4 v[14:15], v[10:13], off
	v_lshlrev_b32_e32 v14, 10, v9
	v_mov_b32_e32 v15, v7
	s_waitcnt lgkmcnt(6)
	v_cvt_pk_bf16_f32 v10, v30, v28
	s_waitcnt lgkmcnt(4)
	v_cvt_pk_bf16_f32 v11, v32, v34
	s_waitcnt lgkmcnt(2)
	v_cvt_pk_bf16_f32 v12, v36, v38
	s_waitcnt lgkmcnt(0)
	v_cvt_pk_bf16_f32 v13, v40, v44
	v_lshl_add_u64 v[14:15], v[42:43], 0, v[14:15]
	v_or_b32_e32 v9, s4, v19
	global_store_dwordx4 v[14:15], v[10:13], off
	v_lshlrev_b32_e32 v14, 10, v9
	v_mov_b32_e32 v15, v7
	v_cvt_pk_bf16_f32 v10, v31, v29
	v_cvt_pk_bf16_f32 v11, v33, v35
	v_cvt_pk_bf16_f32 v12, v37, v39
	v_cvt_pk_bf16_f32 v13, v41, v45
	v_lshl_add_u64 v[14:15], v[42:43], 0, v[14:15]
	global_store_dwordx4 v[14:15], v[10:13], off
	s_waitcnt lgkmcnt(0)

; __device__ __forceinline__ void transpose_item(const float* W, int K, int N, bf16_t* WT, const float* g, LAS float* scr, int item, int lane) {
;     ...
;     for (int i = 0; i < 32; ++i) { const int kk = 2 * i + (lane >> 5); wv[i] = W[(size_t)(k0 + kk) * N + n0 + (lane & 31)]; gl[i] = g ? g[k0 + kk] : 1.0f; }
; #pragma unroll
;     for (int i = 0; i < 32; ++i) { const int kk = 2 * i + (lane >> 5); scr[kk * 33 + (lane & 31)] = wv[i] * gl[i]; }
; __global__ void __launch_bounds__(512, 2) fwd_kernel(Args a_unused) {
;     ...
;             if (r < I_O) { transpose_item(A->w_ob + (size_t)l * 512 * 1024, 512, 1024, WO3 + (size_t)(l * 3 + 1) * 1024 * 512, nullptr, scr, r, lane); continue; } r -= I_O;
.LBB0_17:
	s_andn2_b64 vcc, exec, s[4:5]
	s_cbranch_vccnz .LBB0_19
	s_load_dwordx2 s[4:5], s[8:9], 0x28
	s_ashr_i32 s23, s22, 31
	s_lshl_b64 s[24:25], s[22:23], 21
	s_mul_i32 s6, s22, 3
	v_mov_b32_e32 v13, v7
	s_waitcnt lgkmcnt(0)
	s_add_u32 s13, s4, s24
	s_addc_u32 s16, s5, s25
	s_ashr_i32 s7, s6, 31
	s_lshl_b64 s[6:7], s[6:7], 20
	s_add_u32 s5, s27, s6
	s_addc_u32 s6, s28, s7
	s_lshl_b32 s4, s12, 1
	s_and_b32 s23, s4, 0x1c0
	s_lshl_b32 s4, s64, 5
	s_and_b32 s4, s4, 0x3e0
	s_xor_b32 s7, s23, 0x100
	v_bitop3_b32 v9, s23, v1, v27 bitop3:0xde
	s_lshl_b32 s23, s4, 2
	s_add_u32 s24, s13, s23
	s_addc_u32 s25, s16, 0
	v_lshl_add_u64 v[10:11], s[24:25], 0, v[6:7]
	v_lshlrev_b32_e32 v12, 12, v9
	v_lshl_add_u64 v[10:11], v[10:11], 0, v[12:13]
	v_add_co_u32_e32 v12, vcc, s31, v10
	s_lshl_b32 s7, s7, 1
	s_nop 0
	v_addc_co_u32_e32 v13, vcc, 0, v11, vcc
	v_add_co_u32_e32 v14, vcc, s33, v10
	s_add_u32 s24, s5, s7
	s_nop 0
	v_addc_co_u32_e32 v15, vcc, 0, v11, vcc
	v_add_co_u32_e32 v28, vcc, s34, v10
	s_addc_u32 s25, s6, 0
	s_nop 0
	v_addc_co_u32_e32 v29, vcc, 0, v11, vcc
	v_add_co_u32_e32 v30, vcc, s35, v10
	s_nop 1
	v_addc_co_u32_e32 v31, vcc, 0, v11, vcc
	v_add_co_u32_e32 v32, vcc, s36, v10
	s_nop 1
	v_addc_co_u32_e32 v33, vcc, 0, v11, vcc
	v_add_co_u32_e32 v34, vcc, s37, v10
	s_nop 1
	v_addc_co_u32_e32 v35, vcc, 0, v11, vcc
	v_add_co_u32_e32 v36, vcc, s38, v10
	s_nop 1
	v_addc_co_u32_e32 v37, vcc, 0, v11, vcc
	global_load_dword v9, v[10:11], off nt
	global_load_dword v40, v[12:13], off nt
	global_load_dword v41, v[14:15], off nt
	global_load_dword v42, v[28:29], off nt
	global_load_dword v43, v[30:31], off nt
	global_load_dword v44, v[32:33], off nt
	global_load_dword v45, v[34:35], off nt
	global_load_dword v46, v[36:37], off nt
	v_add_co_u32_e32 v12, vcc, s39, v10
	s_nop 1
	v_addc_co_u32_e32 v13, vcc, 0, v11, vcc
	v_add_co_u32_e32 v14, vcc, s40, v10
	s_nop 1
	v_addc_co_u32_e32 v15, vcc, 0, v11, vcc
	v_add_co_u32_e32 v28, vcc, s41, v10
	s_nop 1
	v_addc_co_u32_e32 v29, vcc, 0, v11, vcc
	v_add_co_u32_e32 v30, vcc, s42, v10
	s_nop 1
	v_addc_co_u32_e32 v31, vcc, 0, v11, vcc
	v_add_co_u32_e32 v32, vcc, s43, v10
	s_nop 1
	v_addc_co_u32_e32 v33, vcc, 0, v11, vcc
	v_add_co_u32_e32 v34, vcc, s44, v10
	s_nop 1
	v_addc_co_u32_e32 v35, vcc, 0, v11, vcc
	v_add_co_u32_e32 v36, vcc, s45, v10
	s_nop 1
	v_addc_co_u32_e32 v37, vcc, 0, v11, vcc
	v_add_co_u32_e32 v38, vcc, s46, v10
	s_nop 1
	v_addc_co_u32_e32 v39, vcc, 0, v11, vcc
	global_load_dword v47, v[12:13], off nt
	global_load_dword v48, v[14:15], off nt
	global_load_dword v49, v[28:29], off nt
	global_load_dword v50, v[30:31], off nt
	global_load_dword v51, v[32:33], off nt
	global_load_dword v52, v[34:35], off nt
	global_load_dword v53, v[36:37], off nt
	global_load_dword v54, v[38:39], off nt
	v_add_co_u32_e32 v12, vcc, s47, v10
	s_nop 1
	v_addc_co_u32_e32 v13, vcc, 0, v11, vcc
	v_add_co_u32_e32 v14, vcc, s48, v10
	s_nop 1
	v_addc_co_u32_e32 v15, vcc, 0, v11, vcc
	v_add_co_u32_e32 v28, vcc, s49, v10
	s_nop 1
	v_addc_co_u32_e32 v29, vcc, 0, v11, vcc
	v_add_co_u32_e32 v30, vcc, s50, v10
	s_nop 1
	v_addc_co_u32_e32 v31, vcc, 0, v11, vcc
	v_add_co_u32_e32 v32, vcc, s51, v10
	s_nop 1
	v_addc_co_u32_e32 v33, vcc, 0, v11, vcc
	v_add_co_u32_e32 v34, vcc, s52, v10
	s_nop 1
	v_addc_co_u32_e32 v35, vcc, 0, v11, vcc
	v_add_co_u32_e32 v36, vcc, s53, v10
	s_nop 1
	v_addc_co_u32_e32 v37, vcc, 0, v11, vcc
	v_add_co_u32_e32 v38, vcc, s54, v10
	s_nop 1
	v_addc_co_u32_e32 v39, vcc, 0, v11, vcc
	global_load_dword v55, v[12:13], off nt
	global_load_dword v56, v[14:15], off nt
	global_load_dword v57, v[28:29], off nt
	global_load_dword v58, v[30:31], off nt
	global_load_dword v59, v[32:33], off nt
	global_load_dword v60, v[34:35], off nt
	global_load_dword v61, v[36:37], off nt
	s_nop 0
	global_load_dword v38, v[38:39], off nt
	v_add_co_u32_e32 v12, vcc, s55, v10
	s_nop 1
	v_addc_co_u32_e32 v13, vcc, 0, v11, vcc
	v_add_co_u32_e32 v14, vcc, s56, v10
	s_nop 1
	v_addc_co_u32_e32 v15, vcc, 0, v11, vcc
	v_add_co_u32_e32 v28, vcc, s57, v10
	s_nop 1
	v_addc_co_u32_e32 v29, vcc, 0, v11, vcc
	v_add_co_u32_e32 v30, vcc, s58, v10
	s_nop 1
	v_addc_co_u32_e32 v31, vcc, 0, v11, vcc
	v_add_co_u32_e32 v32, vcc, s59, v10
	s_nop 1
	v_addc_co_u32_e32 v33, vcc, 0, v11, vcc
	v_add_co_u32_e32 v34, vcc, s60, v10
	s_nop 1
	v_addc_co_u32_e32 v35, vcc, 0, v11, vcc
	v_add_co_u32_e32 v36, vcc, s61, v10
	s_nop 1
	v_addc_co_u32_e32 v37, vcc, 0, v11, vcc
	v_add_co_u32_e32 v10, vcc, s62, v10
	s_nop 1
	v_addc_co_u32_e32 v11, vcc, 0, v11, vcc
	global_load_dword v12, v[12:13], off nt
	s_nop 0
	global_load_dword v13, v[14:15], off nt
	s_nop 0
	global_load_dword v14, v[28:29], off nt
	global_load_dword v15, v[30:31], off nt
	s_nop 0
	global_load_dword v28, v[32:33], off nt
	global_load_dword v29, v[34:35], off nt
	global_load_dword v30, v[36:37], off nt
	s_nop 0
	global_load_dword v10, v[10:11], off nt
	s_waitcnt vmcnt(30)
; #define LAS __attribute__((address_space(3)))
; __device__ __forceinline__ unsigned cvtpk(float lo, float hi) { f32x2 v = {lo, hi}; bf16x2_t b = __builtin_convertvector(v, bf16x2_t); return __builtin_bit_cast(unsigned, b); }
; __device__ __forceinline__ void transpose_item(const float* W, int K, int N, bf16_t* WT, const float* g, LAS float* scr, int item, int lane) {
;     ...
;     for (int i = 0; i < 32; ++i) { const int kk = 2 * i + (lane >> 5); scr[kk * 33 + (lane & 31)] = wv[i] * gl[i]; }
;     asm volatile("s_waitcnt lgkmcnt(0)" ::: "memory");
;     const int c = lane & 7;
; #pragma unroll
;     for (int j = 0; j < 4; ++j) { const int n = (lane >> 3) + 8 * j; const LAS float* s = scr + (8 * c) * 33 + n;
;         u32x4 o; o.x = cvtpk(s[0 * 33], s[1 * 33]); o.y = cvtpk(s[2 * 33], s[3 * 33]); o.z = cvtpk(s[4 * 33], s[5 * 33]); o.w = cvtpk(s[6 * 33], s[7 * 33]);
;         *(u32x4*)(WT + (size_t)(n0 + n) * K + k0 + 8 * c) = o; }
;     asm volatile("s_waitcnt lgkmcnt(0)" ::: "memory");
	ds_write2_b32 v3, v9, v40 offset1:66
	s_waitcnt vmcnt(28)
	ds_write2_b32 v3, v41, v42 offset0:132 offset1:198
	s_waitcnt vmcnt(26)
	ds_write2_b32 v20, v43, v44 offset0:8 offset1:74
	s_waitcnt vmcnt(24)
	ds_write2_b32 v20, v45, v46 offset0:140 offset1:206
	s_waitcnt vmcnt(22)
	ds_write2_b32 v21, v47, v48 offset0:16 offset1:82
	s_waitcnt vmcnt(20)
	ds_write2_b32 v21, v49, v50 offset0:148 offset1:214
	s_waitcnt vmcnt(18)
	ds_write2_b32 v22, v51, v52 offset0:24 offset1:90
	s_waitcnt vmcnt(16)
	ds_write2_b32 v22, v53, v54 offset0:156 offset1:222
	s_waitcnt vmcnt(14)
	ds_write2_b32 v23, v55, v56 offset0:32 offset1:98
	s_waitcnt vmcnt(12)
	ds_write2_b32 v23, v57, v58 offset0:164 offset1:230
	s_waitcnt vmcnt(10)
	ds_write2_b32 v24, v59, v60 offset0:40 offset1:106
	s_waitcnt vmcnt(8)
	ds_write2_b32 v24, v61, v38 offset0:172 offset1:238
	s_waitcnt vmcnt(6)
	ds_write2_b32 v25, v12, v13 offset0:48 offset1:114
	s_waitcnt vmcnt(4)
	ds_write2_b32 v25, v14, v15 offset0:180 offset1:246
	s_waitcnt vmcnt(2)
	ds_write2_b32 v26, v28, v29 offset0:56 offset1:122
	s_waitcnt vmcnt(0)
	ds_write2_b32 v26, v30, v10 offset0:188 offset1:254
	s_waitcnt lgkmcnt(0)
	ds_read2_b32 v[14:15], v16 offset0:33 offset1:41
	ds_read2_b32 v[28:29], v16 offset1:8
	ds_read2_b32 v[30:31], v16 offset0:66 offset1:74
	ds_read2_b32 v[32:33], v16 offset0:99 offset1:107
	ds_read2_b32 v[34:35], v16 offset0:132 offset1:140
	ds_read2_b32 v[36:37], v16 offset0:165 offset1:173
	ds_read2_b32 v[38:39], v16 offset0:198 offset1:206
	ds_read2_b32 v[40:41], v16 offset0:231 offset1:239
	v_mov_b32_e32 v9, v7
	v_lshl_add_u64 v[10:11], s[24:25], 0, v[8:9]
	v_or_b32_e32 v9, s4, v5
	v_lshl_add_u64 v[42:43], v[10:11], 0, s[14:15]
	v_lshlrev_b32_e32 v44, 10, v9
	v_mov_b32_e32 v45, v7
	s_waitcnt lgkmcnt(6)
	v_cvt_pk_bf16_f32 v10, v28, v14
	s_waitcnt lgkmcnt(4)
	v_cvt_pk_bf16_f32 v11, v30, v32
	s_waitcnt lgkmcnt(2)
	v_cvt_pk_bf16_f32 v12, v34, v36
	s_waitcnt lgkmcnt(0)
	v_cvt_pk_bf16_f32 v13, v38, v40
	v_lshl_add_u64 v[44:45], v[42:43], 0, v[44:45]
	global_store_dwordx4 v[44:45], v[10:13], off
	v_or_b32_e32 v9, s4, v17
	v_lshlrev_b32_e32 v14, 10, v9
	v_cvt_pk_bf16_f32 v10, v29, v15
	v_cvt_pk_bf16_f32 v11, v31, v33
	v_cvt_pk_bf16_f32 v12, v35, v37
	v_cvt_pk_bf16_f32 v13, v39, v41
	ds_read2_b32 v[28:29], v16 offset0:49 offset1:57
	ds_read2_b32 v[30:31], v16 offset0:16 offset1:24
	ds_read2_b32 v[32:33], v16 offset0:82 offset1:90
	ds_read2_b32 v[34:35], v16 offset0:115 offset1:123
	ds_read2_b32 v[36:37], v16 offset0:148 offset1:156
	ds_read2_b32 v[38:39], v16 offset0:181 offset1:189
	ds_read2_b32 v[40:41], v16 offset0:214 offset1:222
	ds_read2_b32 v[44:45], v16 offset0:247 offset1:255
	v_mov_b32_e32 v15, v7
	v_lshl_add_u64 v[14:15], v[42:43], 0, v[14:15]
	v_or_b32_e32 v9, s4, v18
	global_store_dwordx4 v[14:15], v[10:13], off
	v_lshlrev_b32_e32 v14, 10, v9
	v_mov_b32_e32 v15, v7
	s_waitcnt lgkmcnt(6)
	v_cvt_pk_bf16_f32 v10, v30, v28
	s_waitcnt lgkmcnt(4)
	v_cvt_pk_bf16_f32 v11, v32, v34
	s_waitcnt lgkmcnt(2)
	v_cvt_pk_bf16_f32 v12, v36, v38
	s_waitcnt lgkmcnt(0)
	v_cvt_pk_bf16_f32 v13, v40, v44
	v_lshl_add_u64 v[14:15], v[42:43], 0, v[14:15]
	v_or_b32_e32 v9, s4, v19
	global_store_dwordx4 v[14:15], v[10:13], off
	v_lshlrev_b32_e32 v14, 10, v9
	v_mov_b32_e32 v15, v7
	v_cvt_pk_bf16_f32 v10, v31, v29
	v_cvt_pk_bf16_f32 v11, v33, v35
	v_cvt_pk_bf16_f32 v12, v37, v39
	v_cvt_pk_bf16_f32 v13, v41, v45
	v_lshl_add_u64 v[14:15], v[42:43], 0, v[14:15]
	global_store_dwordx4 v[14:15], v[10:13], off
	s_waitcnt lgkmcnt(0)

; __device__ __forceinline__ void transpose_item(const float* W, int K, int N, bf16_t* WT, const float* g, LAS float* scr, int item, int lane) {
;     ...
;     for (int i = 0; i < 32; ++i) { const int kk = 2 * i + (lane >> 5); wv[i] = W[(size_t)(k0 + kk) * N + n0 + (lane & 31)]; gl[i] = g ? g[k0 + kk] : 1.0f; }
; #pragma unroll
;     for (int i = 0; i < 32; ++i) { const int kk = 2 * i + (lane >> 5); scr[kk * 33 + (lane & 31)] = wv[i] * gl[i]; }
; __global__ void __launch_bounds__(512, 2) fwd_kernel(Args a_unused) {
;     ...
;             if (r < I_O) { transpose_item(A->w_oa + (size_t)l * 512 * 1024, 512, 1024, WO3 + (size_t)(l * 3 + 0) * 1024 * 512, nullptr, scr, r, lane); continue; } r -= I_O;
.LBB0_20:
	s_andn2_b64 vcc, exec, s[4:5]
	s_cbranch_vccnz .LBB0_22
	s_load_dwordx2 s[4:5], s[8:9], 0x20
	s_ashr_i32 s23, s22, 31
	s_lshl_b64 s[24:25], s[22:23], 21
	s_mul_i32 s6, s22, 3
	v_mov_b32_e32 v13, v7
	s_waitcnt lgkmcnt(0)
	s_add_u32 s13, s4, s24
	s_addc_u32 s16, s5, s25
	s_ashr_i32 s7, s6, 31
	s_lshl_b64 s[6:7], s[6:7], 20
	s_add_u32 s5, s27, s6
	s_addc_u32 s6, s28, s7
	s_lshl_b32 s4, s12, 1
	s_and_b32 s23, s4, 0x1c0
	s_lshl_b32 s4, s64, 5
	s_and_b32 s4, s4, 0x3e0
	s_xor_b32 s7, s23, 0x100
	v_bitop3_b32 v9, s23, v1, v27 bitop3:0xde
	s_lshl_b32 s23, s4, 2
	s_add_u32 s24, s13, s23
	s_addc_u32 s25, s16, 0
	v_lshl_add_u64 v[10:11], s[24:25], 0, v[6:7]
	v_lshlrev_b32_e32 v12, 12, v9
	v_lshl_add_u64 v[10:11], v[10:11], 0, v[12:13]
	v_add_co_u32_e32 v12, vcc, s31, v10
	s_lshl_b32 s7, s7, 1
	s_nop 0
	v_addc_co_u32_e32 v13, vcc, 0, v11, vcc
	v_add_co_u32_e32 v14, vcc, s33, v10
	s_add_u32 s24, s5, s7
	s_nop 0
	v_addc_co_u32_e32 v15, vcc, 0, v11, vcc
	v_add_co_u32_e32 v28, vcc, s34, v10
	s_addc_u32 s25, s6, 0
	s_nop 0
	v_addc_co_u32_e32 v29, vcc, 0, v11, vcc
	v_add_co_u32_e32 v30, vcc, s35, v10
	s_nop 1
	v_addc_co_u32_e32 v31, vcc, 0, v11, vcc
	v_add_co_u32_e32 v32, vcc, s36, v10
	s_nop 1
	v_addc_co_u32_e32 v33, vcc, 0, v11, vcc
	v_add_co_u32_e32 v34, vcc, s37, v10
	s_nop 1
	v_addc_co_u32_e32 v35, vcc, 0, v11, vcc
	v_add_co_u32_e32 v36, vcc, s38, v10
	s_nop 1
	v_addc_co_u32_e32 v37, vcc, 0, v11, vcc
	global_load_dword v9, v[10:11], off nt
	global_load_dword v40, v[12:13], off nt
	global_load_dword v41, v[14:15], off nt
	global_load_dword v42, v[28:29], off nt
	global_load_dword v43, v[30:31], off nt
	global_load_dword v44, v[32:33], off nt
	global_load_dword v45, v[34:35], off nt
	global_load_dword v46, v[36:37], off nt
	v_add_co_u32_e32 v12, vcc, s39, v10
	s_nop 1
	v_addc_co_u32_e32 v13, vcc, 0, v11, vcc
	v_add_co_u32_e32 v14, vcc, s40, v10
	s_nop 1
	v_addc_co_u32_e32 v15, vcc, 0, v11, vcc
	v_add_co_u32_e32 v28, vcc, s41, v10
	s_nop 1
	v_addc_co_u32_e32 v29, vcc, 0, v11, vcc
	v_add_co_u32_e32 v30, vcc, s42, v10
	s_nop 1
	v_addc_co_u32_e32 v31, vcc, 0, v11, vcc
	v_add_co_u32_e32 v32, vcc, s43, v10
	s_nop 1
	v_addc_co_u32_e32 v33, vcc, 0, v11, vcc
	v_add_co_u32_e32 v34, vcc, s44, v10
	s_nop 1
	v_addc_co_u32_e32 v35, vcc, 0, v11, vcc
	v_add_co_u32_e32 v36, vcc, s45, v10
	s_nop 1
	v_addc_co_u32_e32 v37, vcc, 0, v11, vcc
	v_add_co_u32_e32 v38, vcc, s46, v10
	s_nop 1
	v_addc_co_u32_e32 v39, vcc, 0, v11, vcc
	global_load_dword v47, v[12:13], off nt
	global_load_dword v48, v[14:15], off nt
	global_load_dword v49, v[28:29], off nt
	global_load_dword v50, v[30:31], off nt
	global_load_dword v51, v[32:33], off nt
	global_load_dword v52, v[34:35], off nt
	global_load_dword v53, v[36:37], off nt
	global_load_dword v54, v[38:39], off nt
	v_add_co_u32_e32 v12, vcc, s47, v10
	s_nop 1
	v_addc_co_u32_e32 v13, vcc, 0, v11, vcc
	v_add_co_u32_e32 v14, vcc, s48, v10
	s_nop 1
	v_addc_co_u32_e32 v15, vcc, 0, v11, vcc
	v_add_co_u32_e32 v28, vcc, s49, v10
	s_nop 1
	v_addc_co_u32_e32 v29, vcc, 0, v11, vcc
	v_add_co_u32_e32 v30, vcc, s50, v10
	s_nop 1
	v_addc_co_u32_e32 v31, vcc, 0, v11, vcc
	v_add_co_u32_e32 v32, vcc, s51, v10
	s_nop 1
	v_addc_co_u32_e32 v33, vcc, 0, v11, vcc
	v_add_co_u32_e32 v34, vcc, s52, v10
	s_nop 1
	v_addc_co_u32_e32 v35, vcc, 0, v11, vcc
	v_add_co_u32_e32 v36, vcc, s53, v10
	s_nop 1
	v_addc_co_u32_e32 v37, vcc, 0, v11, vcc
	v_add_co_u32_e32 v38, vcc, s54, v10
	s_nop 1
	v_addc_co_u32_e32 v39, vcc, 0, v11, vcc
	global_load_dword v55, v[12:13], off nt
	global_load_dword v56, v[14:15], off nt
	global_load_dword v57, v[28:29], off nt
	global_load_dword v58, v[30:31], off nt
	global_load_dword v59, v[32:33], off nt
	global_load_dword v60, v[34:35], off nt
	global_load_dword v61, v[36:37], off nt
	s_nop 0
	global_load_dword v38, v[38:39], off nt
	v_add_co_u32_e32 v12, vcc, s55, v10
	s_nop 1
	v_addc_co_u32_e32 v13, vcc, 0, v11, vcc
	v_add_co_u32_e32 v14, vcc, s56, v10
	s_nop 1
	v_addc_co_u32_e32 v15, vcc, 0, v11, vcc
	v_add_co_u32_e32 v28, vcc, s57, v10
	s_nop 1
	v_addc_co_u32_e32 v29, vcc, 0, v11, vcc
	v_add_co_u32_e32 v30, vcc, s58, v10
	s_nop 1
	v_addc_co_u32_e32 v31, vcc, 0, v11, vcc
	v_add_co_u32_e32 v32, vcc, s59, v10
	s_nop 1
	v_addc_co_u32_e32 v33, vcc, 0, v11, vcc
	v_add_co_u32_e32 v34, vcc, s60, v10
	s_nop 1
	v_addc_co_u32_e32 v35, vcc, 0, v11, vcc
	v_add_co_u32_e32 v36, vcc, s61, v10
	s_nop 1
	v_addc_co_u32_e32 v37, vcc, 0, v11, vcc
	v_add_co_u32_e32 v10, vcc, s62, v10
	s_nop 1
	v_addc_co_u32_e32 v11, vcc, 0, v11, vcc
	global_load_dword v12, v[12:13], off nt
	s_nop 0
	global_load_dword v13, v[14:15], off nt
	s_nop 0
	global_load_dword v14, v[28:29], off nt
	global_load_dword v15, v[30:31], off nt
	s_nop 0
	global_load_dword v28, v[32:33], off nt
	global_load_dword v29, v[34:35], off nt
	global_load_dword v30, v[36:37], off nt
	s_nop 0
	global_load_dword v10, v[10:11], off nt
	s_waitcnt vmcnt(30)
; #define LAS __attribute__((address_space(3)))
; __device__ __forceinline__ unsigned cvtpk(float lo, float hi) { f32x2 v = {lo, hi}; bf16x2_t b = __builtin_convertvector(v, bf16x2_t); return __builtin_bit_cast(unsigned, b); }
; __device__ __forceinline__ void transpose_item(const float* W, int K, int N, bf16_t* WT, const float* g, LAS float* scr, int item, int lane) {
;     ...
;     for (int i = 0; i < 32; ++i) { const int kk = 2 * i + (lane >> 5); scr[kk * 33 + (lane & 31)] = wv[i] * gl[i]; }
;     asm volatile("s_waitcnt lgkmcnt(0)" ::: "memory");
;     const int c = lane & 7;
; #pragma unroll
;     for (int j = 0; j < 4; ++j) { const int n = (lane >> 3) + 8 * j; const LAS float* s = scr + (8 * c) * 33 + n;
;         u32x4 o; o.x = cvtpk(s[0 * 33], s[1 * 33]); o.y = cvtpk(s[2 * 33], s[3 * 33]); o.z = cvtpk(s[4 * 33], s[5 * 33]); o.w = cvtpk(s[6 * 33], s[7 * 33]);
;         *(u32x4*)(WT + (size_t)(n0 + n) * K + k0 + 8 * c) = o; }
;     asm volatile("s_waitcnt lgkmcnt(0)" ::: "memory");
	ds_write2_b32 v3, v9, v40 offset1:66
	s_waitcnt vmcnt(28)
	ds_write2_b32 v3, v41, v42 offset0:132 offset1:198
	s_waitcnt vmcnt(26)
	ds_write2_b32 v20, v43, v44 offset0:8 offset1:74
	s_waitcnt vmcnt(24)
	ds_write2_b32 v20, v45, v46 offset0:140 offset1:206
	s_waitcnt vmcnt(22)
	ds_write2_b32 v21, v47, v48 offset0:16 offset1:82
	s_waitcnt vmcnt(20)
	ds_write2_b32 v21, v49, v50 offset0:148 offset1:214
	s_waitcnt vmcnt(18)
	ds_write2_b32 v22, v51, v52 offset0:24 offset1:90
	s_waitcnt vmcnt(16)
	ds_write2_b32 v22, v53, v54 offset0:156 offset1:222
	s_waitcnt vmcnt(14)
	ds_write2_b32 v23, v55, v56 offset0:32 offset1:98
	s_waitcnt vmcnt(12)
	ds_write2_b32 v23, v57, v58 offset0:164 offset1:230
	s_waitcnt vmcnt(10)
	ds_write2_b32 v24, v59, v60 offset0:40 offset1:106
	s_waitcnt vmcnt(8)
	ds_write2_b32 v24, v61, v38 offset0:172 offset1:238
	s_waitcnt vmcnt(6)
	ds_write2_b32 v25, v12, v13 offset0:48 offset1:114
	s_waitcnt vmcnt(4)
	ds_write2_b32 v25, v14, v15 offset0:180 offset1:246
	s_waitcnt vmcnt(2)
	ds_write2_b32 v26, v28, v29 offset0:56 offset1:122
	s_waitcnt vmcnt(0)
	ds_write2_b32 v26, v30, v10 offset0:188 offset1:254
	s_waitcnt lgkmcnt(0)
	ds_read2_b32 v[14:15], v16 offset0:33 offset1:41
	ds_read2_b32 v[28:29], v16 offset1:8
	ds_read2_b32 v[30:31], v16 offset0:66 offset1:74
	ds_read2_b32 v[32:33], v16 offset0:99 offset1:107
	ds_read2_b32 v[34:35], v16 offset0:132 offset1:140
	ds_read2_b32 v[36:37], v16 offset0:165 offset1:173
	ds_read2_b32 v[38:39], v16 offset0:198 offset1:206
	ds_read2_b32 v[40:41], v16 offset0:231 offset1:239
	v_mov_b32_e32 v9, v7
	v_lshl_add_u64 v[42:43], s[24:25], 0, v[8:9]
	v_or_b32_e32 v9, s4, v5
	v_lshlrev_b32_e32 v44, 10, v9
	v_mov_b32_e32 v45, v7
	s_waitcnt lgkmcnt(6)
	v_cvt_pk_bf16_f32 v10, v28, v14
	s_waitcnt lgkmcnt(4)
	v_cvt_pk_bf16_f32 v11, v30, v32
	s_waitcnt lgkmcnt(2)
	v_cvt_pk_bf16_f32 v12, v34, v36
	s_waitcnt lgkmcnt(0)
	v_cvt_pk_bf16_f32 v13, v38, v40
	v_lshl_add_u64 v[44:45], v[42:43], 0, v[44:45]
	global_store_dwordx4 v[44:45], v[10:13], off
	v_or_b32_e32 v9, s4, v17
	v_lshlrev_b32_e32 v14, 10, v9
	v_cvt_pk_bf16_f32 v10, v29, v15
	v_cvt_pk_bf16_f32 v11, v31, v33
	v_cvt_pk_bf16_f32 v12, v35, v37
	v_cvt_pk_bf16_f32 v13, v39, v41
	ds_read2_b32 v[28:29], v16 offset0:49 offset1:57
	ds_read2_b32 v[30:31], v16 offset0:16 offset1:24
	ds_read2_b32 v[32:33], v16 offset0:82 offset1:90
	ds_read2_b32 v[34:35], v16 offset0:115 offset1:123
	ds_read2_b32 v[36:37], v16 offset0:148 offset1:156
	ds_read2_b32 v[38:39], v16 offset0:181 offset1:189
	ds_read2_b32 v[40:41], v16 offset0:214 offset1:222
	ds_read2_b32 v[44:45], v16 offset0:247 offset1:255
	v_mov_b32_e32 v15, v7
	v_lshl_add_u64 v[14:15], v[42:43], 0, v[14:15]
	v_or_b32_e32 v9, s4, v18
	global_store_dwordx4 v[14:15], v[10:13], off
	v_lshlrev_b32_e32 v14, 10, v9
	v_mov_b32_e32 v15, v7
	s_waitcnt lgkmcnt(6)
	v_cvt_pk_bf16_f32 v10, v30, v28
	s_waitcnt lgkmcnt(4)
	v_cvt_pk_bf16_f32 v11, v32, v34
	s_waitcnt lgkmcnt(2)
	v_cvt_pk_bf16_f32 v12, v36, v38
	s_waitcnt lgkmcnt(0)
	v_cvt_pk_bf16_f32 v13, v40, v44
	v_lshl_add_u64 v[14:15], v[42:43], 0, v[14:15]
	v_or_b32_e32 v9, s4, v19
	global_store_dwordx4 v[14:15], v[10:13], off
	v_lshlrev_b32_e32 v14, 10, v9
	v_mov_b32_e32 v15, v7
	v_cvt_pk_bf16_f32 v10, v31, v29
	v_cvt_pk_bf16_f32 v11, v33, v35
	v_cvt_pk_bf16_f32 v12, v37, v39
	v_cvt_pk_bf16_f32 v13, v41, v45
	v_lshl_add_u64 v[14:15], v[42:43], 0, v[14:15]
	global_store_dwordx4 v[14:15], v[10:13], off
	s_waitcnt lgkmcnt(0)

; __device__ __forceinline__ void transpose_item(const float* W, int K, int N, bf16_t* WT, const float* g, LAS float* scr, int item, int lane) {
;     const int nblk = N / 32, kb = item / nblk, nb = item % nblk, k0 = 64 * kb, n0 = 32 * nb;
;     float wv[32], gl[32];
; #pragma unroll
;     for (int i = 0; i < 32; ++i) { const int kk = 2 * i + (lane >> 5); wv[i] = W[(size_t)(k0 + kk) * N + n0 + (lane & 31)]; gl[i] = g ? g[k0 + kk] : 1.0f; }
; #pragma unroll
;     for (int i = 0; i < 32; ++i) { const int kk = 2 * i + (lane >> 5); scr[kk * 33 + (lane & 31)] = wv[i] * gl[i]; }
.LBB0_23:
	s_andn2_b64 vcc, exec, s[4:5]
	s_cbranch_vccnz .LBB0_8
	s_load_dwordx4 s[4:7], s[8:9], 0x10
	s_mul_i32 s16, s22, 0x2d00000
	s_mul_hi_i32 s13, s22, 0x2d00000
	s_mul_hi_i32 s23, s12, 0xb60b60b7
	v_mov_b32_e32 v28, 1.0
	s_waitcnt lgkmcnt(0)
	s_add_u32 s16, s6, s16
	s_addc_u32 s25, s7, s13
	s_lshl_b32 s6, s22, 10
	s_ashr_i32 s7, s6, 31
	s_lshl_b64 s[6:7], s[6:7], 2
	s_add_u32 s66, s4, s6
	s_addc_u32 s67, s5, s7
	s_add_i32 s23, s23, s12
	s_lshr_b32 s6, s23, 31
	s_ashr_i32 s7, s23, 8
	s_add_i32 s6, s7, s6
	s_mul_i32 s7, s6, 0x168
	s_sub_i32 s7, s12, s7
	s_lshl_b32 s24, s6, 6
	s_lshl_b32 s6, s7, 5
	s_ashr_i32 s7, s6, 31
	s_lshl_b64 s[12:13], s[6:7], 2
	s_add_u32 s12, s16, s12
	s_addc_u32 s13, s25, s13
	v_or_b32_e32 v10, s24, v1
	v_lshl_add_u64 v[12:13], s[12:13], 0, v[6:7]
	v_mad_i64_i32 v[14:15], s[12:13], v10, s63, v[12:13]
	global_load_dword v9, v[14:15], off nt
	s_cmp_lg_u64 s[4:5], 0
	v_ashrrev_i32_e32 v11, 31, v10
	s_cselect_b64 s[12:13], -1, 0
	s_cmp_eq_u64 s[4:5], 0
	v_lshl_add_u64 v[14:15], v[10:11], 2, s[66:67]
	v_mov_b32_e32 v11, 1.0
	s_cbranch_scc1 .LBB0_26
	global_load_dword v11, v[14:15], off nt
.LBB0_26:
	v_or_b32_e32 v29, 2, v10
	v_mad_i64_i32 v[30:31], s[4:5], v29, s63, v[12:13]
	global_load_dword v29, v[30:31], off nt
	v_cndmask_b32_e64 v30, 0, 1, s[12:13]
	v_cmp_ne_u32_e64 s[4:5], 1, v30
	s_andn2_b64 vcc, exec, s[12:13]
	s_cbranch_vccnz .LBB0_28
	global_load_dword v28, v[14:15], off offset:8 nt
.LBB0_28:
	v_or_b32_e32 v30, 4, v10
	v_mad_i64_i32 v[30:31], s[12:13], v30, s63, v[12:13]
	global_load_dword v30, v[30:31], off nt
	v_mov_b32_e32 v31, 1.0
	s_and_b64 vcc, exec, s[4:5]
	v_mov_b32_e32 v32, 1.0
	s_cbranch_vccnz .LBB0_30
	global_load_dword v32, v[14:15], off offset:16 nt
.LBB0_30:
	v_or_b32_e32 v33, 6, v10
	v_mad_i64_i32 v[34:35], s[12:13], v33, s63, v[12:13]
	global_load_dword v33, v[34:35], off nt
	s_and_b64 vcc, exec, s[4:5]
	s_cbranch_vccnz .LBB0_32
	global_load_dword v31, v[14:15], off offset:24 nt
.LBB0_32:
	v_or_b32_e32 v34, 8, v10
	v_mad_i64_i32 v[34:35], s[12:13], v34, s63, v[12:13]
	global_load_dword v34, v[34:35], off nt
	v_mov_b32_e32 v35, 1.0
	s_and_b64 vcc, exec, s[4:5]
	v_mov_b32_e32 v36, 1.0
	s_cbranch_vccnz .LBB0_34
	global_load_dword v36, v[14:15], off offset:32 nt
.LBB0_34:
	v_or_b32_e32 v37, 10, v10
	v_mad_i64_i32 v[38:39], s[12:13], v37, s63, v[12:13]
	global_load_dword v37, v[38:39], off nt
	s_and_b64 vcc, exec, s[4:5]
	s_cbranch_vccnz .LBB0_36
	global_load_dword v35, v[14:15], off offset:40 nt
.LBB0_36:
	v_or_b32_e32 v38, 12, v10
	v_mad_i64_i32 v[38:39], s[12:13], v38, s63, v[12:13]
	global_load_dword v38, v[38:39], off nt
	v_mov_b32_e32 v39, 1.0
	s_and_b64 vcc, exec, s[4:5]
	v_mov_b32_e32 v40, 1.0
	s_cbranch_vccnz .LBB0_38
	global_load_dword v40, v[14:15], off offset:48 nt
.LBB0_38:
	v_or_b32_e32 v41, 14, v10
	v_mad_i64_i32 v[42:43], s[12:13], v41, s63, v[12:13]
	global_load_dword v41, v[42:43], off nt
	s_and_b64 vcc, exec, s[4:5]
	s_cbranch_vccnz .LBB0_40
	global_load_dword v39, v[14:15], off offset:56 nt
.LBB0_40:
	v_or_b32_e32 v42, 16, v10
	v_mad_i64_i32 v[42:43], s[12:13], v42, s63, v[12:13]
	global_load_dword v42, v[42:43], off nt
	v_mov_b32_e32 v43, 1.0
	s_and_b64 vcc, exec, s[4:5]
	v_mov_b32_e32 v44, 1.0
	s_cbranch_vccnz .LBB0_42
	global_load_dword v44, v[14:15], off offset:64 nt
.LBB0_42:
	v_or_b32_e32 v45, 18, v10
	v_mad_i64_i32 v[46:47], s[12:13], v45, s63, v[12:13]
	global_load_dword v45, v[46:47], off nt
	s_and_b64 vcc, exec, s[4:5]
	s_cbranch_vccnz .LBB0_44
	global_load_dword v43, v[14:15], off offset:72 nt
.LBB0_44:
	v_or_b32_e32 v46, 20, v10
	v_mad_i64_i32 v[46:47], s[12:13], v46, s63, v[12:13]
	global_load_dword v46, v[46:47], off nt
	v_mov_b32_e32 v47, 1.0
	s_and_b64 vcc, exec, s[4:5]
	v_mov_b32_e32 v48, 1.0
	s_cbranch_vccnz .LBB0_46
	global_load_dword v48, v[14:15], off offset:80 nt
.LBB0_46:
	v_or_b32_e32 v49, 22, v10
	v_mad_i64_i32 v[50:51], s[12:13], v49, s63, v[12:13]
	global_load_dword v49, v[50:51], off nt
	s_and_b64 vcc, exec, s[4:5]
	s_cbranch_vccnz .LBB0_48
	global_load_dword v47, v[14:15], off offset:88 nt
.LBB0_48:
	v_or_b32_e32 v50, 24, v10
	v_mad_i64_i32 v[50:51], s[12:13], v50, s63, v[12:13]
	global_load_dword v50, v[50:51], off nt
	v_mov_b32_e32 v51, 1.0
	s_and_b64 vcc, exec, s[4:5]
	v_mov_b32_e32 v52, 1.0
	s_cbranch_vccnz .LBB0_50
	global_load_dword v52, v[14:15], off offset:96 nt
.LBB0_50:
	v_or_b32_e32 v53, 26, v10
	v_mad_i64_i32 v[54:55], s[12:13], v53, s63, v[12:13]
	global_load_dword v53, v[54:55], off nt
	s_and_b64 vcc, exec, s[4:5]
	s_cbranch_vccnz .LBB0_52
	global_load_dword v51, v[14:15], off offset:104 nt
; __device__ __forceinline__ void transpose_item(const float* W, int K, int N, bf16_t* WT, const float* g, LAS float* scr, int item, int lane) {
;     const int nblk = N / 32, kb = item / nblk, nb = item % nblk, k0 = 64 * kb, n0 = 32 * nb;
;     float wv[32], gl[32];
; #pragma unroll
;     for (int i = 0; i < 32; ++i) { const int kk = 2 * i + (lane >> 5); wv[i] = W[(size_t)(k0 + kk) * N + n0 + (lane & 31)]; gl[i] = g ? g[k0 + kk] : 1.0f; }
; #pragma unroll
;     for (int i = 0; i < 32; ++i) { const int kk = 2 * i + (lane >> 5); scr[kk * 33 + (lane & 31)] = wv[i] * gl[i]; }
.LBB0_52:
	v_or_b32_e32 v54, 28, v10
	v_mad_i64_i32 v[54:55], s[12:13], v54, s63, v[12:13]
	global_load_dword v54, v[54:55], off nt
	v_mov_b32_e32 v55, 1.0
	s_and_b64 vcc, exec, s[4:5]
	v_mov_b32_e32 v56, 1.0
	s_cbranch_vccnz .LBB0_54
	global_load_dword v56, v[14:15], off offset:112 nt
.LBB0_54:
	v_or_b32_e32 v57, 30, v10
	v_mad_i64_i32 v[58:59], s[12:13], v57, s63, v[12:13]
	global_load_dword v57, v[58:59], off nt
	s_and_b64 vcc, exec, s[4:5]
	s_cbranch_vccnz .LBB0_56
	global_load_dword v55, v[14:15], off offset:120 nt
.LBB0_56:
	v_or_b32_e32 v58, 32, v10
	v_mad_i64_i32 v[58:59], s[12:13], v58, s63, v[12:13]
	global_load_dword v58, v[58:59], off nt
	v_mov_b32_e32 v59, 1.0
	s_and_b64 vcc, exec, s[4:5]
	v_mov_b32_e32 v60, 1.0
	s_cbranch_vccnz .LBB0_58
	global_load_dword v60, v[14:15], off offset:128 nt
.LBB0_58:
	v_or_b32_e32 v61, 34, v10
	v_mad_i64_i32 v[62:63], s[12:13], v61, s63, v[12:13]
	global_load_dword v61, v[62:63], off nt
	s_and_b64 vcc, exec, s[4:5]
	s_cbranch_vccnz .LBB0_60
	global_load_dword v59, v[14:15], off offset:136 nt
.LBB0_60:
	v_or_b32_e32 v62, 36, v10
	v_mad_i64_i32 v[62:63], s[12:13], v62, s63, v[12:13]
	global_load_dword v62, v[62:63], off nt
	v_mov_b32_e32 v63, 1.0
	s_and_b64 vcc, exec, s[4:5]
	v_mov_b32_e32 v64, 1.0
	s_cbranch_vccnz .LBB0_62
	global_load_dword v64, v[14:15], off offset:144 nt
.LBB0_62:
	v_or_b32_e32 v65, 38, v10
	v_mad_i64_i32 v[66:67], s[12:13], v65, s63, v[12:13]
	global_load_dword v65, v[66:67], off nt
	s_and_b64 vcc, exec, s[4:5]
	s_cbranch_vccnz .LBB0_64
	global_load_dword v63, v[14:15], off offset:152 nt
.LBB0_64:
	v_or_b32_e32 v66, 40, v10
	v_mad_i64_i32 v[66:67], s[12:13], v66, s63, v[12:13]
	global_load_dword v66, v[66:67], off nt
	v_mov_b32_e32 v67, 1.0
	s_and_b64 vcc, exec, s[4:5]
	v_mov_b32_e32 v68, 1.0
	s_cbranch_vccnz .LBB0_66
	global_load_dword v68, v[14:15], off offset:160 nt
.LBB0_66:
	v_or_b32_e32 v69, 42, v10
	v_mad_i64_i32 v[70:71], s[12:13], v69, s63, v[12:13]
	global_load_dword v69, v[70:71], off nt
	s_and_b64 vcc, exec, s[4:5]
	s_cbranch_vccnz .LBB0_68
	global_load_dword v67, v[14:15], off offset:168 nt
.LBB0_68:
	v_or_b32_e32 v70, 44, v10
	v_mad_i64_i32 v[70:71], s[12:13], v70, s63, v[12:13]
	global_load_dword v70, v[70:71], off nt
	v_mov_b32_e32 v71, 1.0
	s_and_b64 vcc, exec, s[4:5]
	v_mov_b32_e32 v72, 1.0
	s_cbranch_vccnz .LBB0_70
	global_load_dword v72, v[14:15], off offset:176 nt
.LBB0_70:
	v_or_b32_e32 v73, 46, v10
	v_mad_i64_i32 v[74:75], s[12:13], v73, s63, v[12:13]
	global_load_dword v73, v[74:75], off nt
	s_and_b64 vcc, exec, s[4:5]
	s_cbranch_vccnz .LBB0_72
	global_load_dword v71, v[14:15], off offset:184 nt
.LBB0_72:
	v_or_b32_e32 v74, 48, v10
	v_mad_i64_i32 v[74:75], s[12:13], v74, s63, v[12:13]
	global_load_dword v74, v[74:75], off nt
	v_mov_b32_e32 v75, 1.0
	s_and_b64 vcc, exec, s[4:5]
	v_mov_b32_e32 v76, 1.0
	s_cbranch_vccnz .LBB0_74
	global_load_dword v76, v[14:15], off offset:192 nt
.LBB0_74:
	v_or_b32_e32 v77, 50, v10
	v_mad_i64_i32 v[78:79], s[12:13], v77, s63, v[12:13]
	global_load_dword v77, v[78:79], off nt
	s_and_b64 vcc, exec, s[4:5]
	s_cbranch_vccnz .LBB0_76
	global_load_dword v75, v[14:15], off offset:200 nt
.LBB0_76:
	v_or_b32_e32 v78, 52, v10
	v_mad_i64_i32 v[78:79], s[12:13], v78, s63, v[12:13]
	global_load_dword v78, v[78:79], off nt
	v_mov_b32_e32 v79, 1.0
	s_and_b64 vcc, exec, s[4:5]
	v_mov_b32_e32 v80, 1.0
	s_cbranch_vccnz .LBB0_78
	global_load_dword v80, v[14:15], off offset:208 nt
.LBB0_78:
	v_or_b32_e32 v81, 54, v10
	v_mad_i64_i32 v[82:83], s[12:13], v81, s63, v[12:13]
	global_load_dword v81, v[82:83], off nt
	s_and_b64 vcc, exec, s[4:5]
	s_cbranch_vccnz .LBB0_80
	global_load_dword v79, v[14:15], off offset:216 nt
.LBB0_80:
	v_or_b32_e32 v82, 56, v10
	v_mad_i64_i32 v[82:83], s[12:13], v82, s63, v[12:13]
	global_load_dword v82, v[82:83], off nt
	v_mov_b32_e32 v83, 1.0
	s_and_b64 vcc, exec, s[4:5]
	v_mov_b32_e32 v84, 1.0
	s_cbranch_vccnz .LBB0_82
	global_load_dword v84, v[14:15], off offset:224 nt
.LBB0_82:
	v_or_b32_e32 v85, 58, v10
	v_mad_i64_i32 v[86:87], s[12:13], v85, s63, v[12:13]
	global_load_dword v85, v[86:87], off nt
	s_and_b64 vcc, exec, s[4:5]
	s_cbranch_vccnz .LBB0_84
	global_load_dword v83, v[14:15], off offset:232 nt
.LBB0_84:
	v_or_b32_e32 v86, 60, v10
	v_mad_i64_i32 v[86:87], s[12:13], v86, s63, v[12:13]
	global_load_dword v86, v[86:87], off nt
	v_mov_b32_e32 v87, 1.0
	s_and_b64 vcc, exec, s[4:5]
	v_mov_b32_e32 v88, 1.0
	s_cbranch_vccnz .LBB0_86
	global_load_dword v88, v[14:15], off offset:240 nt
.LBB0_86:
	v_or_b32_e32 v10, 62, v10
	v_mad_i64_i32 v[12:13], s[12:13], v10, s63, v[12:13]
	global_load_dword v10, v[12:13], off nt
	s_and_b64 vcc, exec, s[4:5]
	s_cbranch_vccnz .LBB0_7
	global_load_dword v87, v[14:15], off offset:248 nt
	s_branch .LBB0_7

; __device__ __forceinline__ unsigned cvtpk(float lo, float hi) { f32x2 v = {lo, hi}; bf16x2_t b = __builtin_convertvector(v, bf16x2_t); return __builtin_bit_cast(unsigned, b); }
; __device__ __forceinline__ void row_to_bf16(const float* xrow, bf16_t* orow, float* ss, int lane) {
;     const f32x4* xr = (const f32x4*)xrow + lane; float s = 0.f;
;     u32x2* o8 = (u32x2*)orow + lane;
;     f32x4 vv[4];
; #pragma unroll
;     for (int j = 0; j < 4; ++j) vv[j] = xr[64 * j];
; #pragma unroll
;     for (int j = 0; j < 4; ++j) { const f32x4 v = vv[j]; s += (v.x * v.x + v.y * v.y) + (v.z * v.z + v.w * v.w); u32x2 w; w.x = cvtpk(v.x, v.y); w.y = cvtpk(v.z, v.w); o8[64 * j] = w; }
;     s = wave_sum(s);
;     if (lane == 0) *ss = s;
; __global__ void __launch_bounds__(512, 2) fwd_kernel(Args a_unused) {
;     ...
;     cg::this_grid().sync();
.LBB0_97:
	s_waitcnt lgkmcnt(0)
	global_load_dwordx4 v[12:15], v4, s[24:25] nt
	global_load_dwordx4 v[16:19], v4, s[24:25] offset:1024 nt
	global_load_dwordx4 v[20:23], v4, s[24:25] offset:2048 nt
	global_load_dwordx4 v[24:27], v4, s[24:25] offset:3072 nt
	s_lshl_b64 s[0:1], s[12:13], 11
	s_waitcnt vmcnt(3)
	v_mul_f32_e32 v28, v13, v13
	v_mul_f32_e32 v29, v15, v15
	s_waitcnt vmcnt(2)
	v_mul_f32_e32 v30, v17, v17
	v_mul_f32_e32 v31, v19, v19
	s_waitcnt vmcnt(1)
	v_mul_f32_e32 v32, v21, v21
	v_mul_f32_e32 v33, v23, v23
	v_fmac_f32_e32 v28, v12, v12
	v_fmac_f32_e32 v29, v14, v14
	v_fmac_f32_e32 v30, v16, v16
	v_fmac_f32_e32 v31, v18, v18
	s_waitcnt vmcnt(0)
	v_mul_f32_e32 v34, v25, v25
	v_mul_f32_e32 v35, v27, v27
	v_fmac_f32_e32 v32, v20, v20
	v_fmac_f32_e32 v33, v22, v22
	v_add_f32_e32 v28, v28, v29
	v_add_f32_e32 v29, v30, v31
	v_fmac_f32_e32 v34, v24, v24
	v_fmac_f32_e32 v35, v26, v26
	v_add_f32_e32 v30, v32, v33
	v_add_f32_e32 v28, v28, v29
	v_add_f32_e32 v28, v28, v30
	v_add_f32_e32 v29, v34, v35
	v_add_f32_e32 v28, v28, v29
	ds_bpermute_b32 v29, v2, v28
	v_cvt_pk_bf16_f32 v12, v12, v13
	v_cvt_pk_bf16_f32 v13, v14, v15
	v_cvt_pk_bf16_f32 v14, v20, v21
	v_cvt_pk_bf16_f32 v15, v22, v23
	s_waitcnt lgkmcnt(0)
	v_add_f32_e32 v28, v28, v29
	ds_bpermute_b32 v29, v5, v28
	s_waitcnt lgkmcnt(0)
	v_add_f32_e32 v30, v28, v29
	ds_bpermute_b32 v31, v8, v30
	v_lshl_add_u64 v[28:29], v[6:7], 0, s[0:1]
	global_store_dwordx2 v[28:29], v[12:13], off
	v_cvt_pk_bf16_f32 v12, v16, v17
	v_cvt_pk_bf16_f32 v13, v18, v19
	s_waitcnt lgkmcnt(0)
	v_add_f32_e32 v30, v30, v31
	ds_bpermute_b32 v31, v9, v30
	global_store_dwordx2 v[28:29], v[12:13], off offset:512
	global_store_dwordx2 v[28:29], v[14:15], off offset:1024
	v_cvt_pk_bf16_f32 v14, v24, v25
	v_cvt_pk_bf16_f32 v15, v26, v27
	s_waitcnt lgkmcnt(0)
	v_add_f32_e32 v16, v30, v31
	ds_bpermute_b32 v17, v10, v16
	global_store_dwordx2 v[28:29], v[14:15], off offset:1536
	s_waitcnt lgkmcnt(0)
	v_add_f32_e32 v12, v16, v17
	ds_bpermute_b32 v13, v11, v12
	s_and_saveexec_b64 s[24:25], s[4:5]
	s_cbranch_execz .LBB0_92
	s_lshl_b64 s[0:1], s[12:13], 2
	s_add_u32 s0, s10, s0
	s_waitcnt lgkmcnt(0)
	v_add_f32_e32 v12, v12, v13
	s_addc_u32 s1, s11, s1
	global_store_dword v3, v12, s[0:1]
	s_branch .LBB0_92
.LBB0_99:
	s_load_dwordx2 s[34:35], s[6:7], 0x0
	s_load_dword s0, s[6:7], 0x8
	v_lshrrev_b32_e32 v2, 20, v0
	v_lshrrev_b32_e32 v0, 10, v0
	v_or_b32_e32 v0, v0, v2
	s_movk_i32 s1, 0x3ff
	v_and_or_b32 v0, v0, s1, v228
	v_cmp_eq_u32_e32 vcc, 0, v0
	s_waitcnt lgkmcnt(0)
	s_barrier
	s_and_saveexec_b64 s[4:5], vcc
	s_cbranch_execz .LBB0_109
	buffer_wbl2 sc1
	s_waitcnt vmcnt(0)
	s_load_dwordx2 s[6:7], s[6:7], 0x58
	v_mov_b32_e32 v3, 0
	s_mov_b64 s[8:9], exec
	v_mbcnt_lo_u32_b32 v2, s8, 0
	v_mbcnt_hi_u32_b32 v2, s9, v2
	s_waitcnt lgkmcnt(0)
	global_load_dword v0, v3, s[6:7] offset:40 nt
	v_cmp_eq_u32_e32 vcc, 0, v2
	s_and_saveexec_b64 s[10:11], vcc
	s_cbranch_execz .LBB0_102
	s_bcnt1_i32_b64 s1, s[8:9]
	v_mov_b32_e32 v4, s1
	global_atomic_add v4, v3, v4, s[6:7] offset:32 sc0
